# stick-breaking units: a workgroup's second unit takes q-block 7-qb instead of the same qb (causal pairing), on top of per-XCD dynamic differential units
# baseline (speedup 1.0000x reference)
.LBB0_584:
	s_ashr_i32 s4, s66, 31
	v_lshrrev_b32_e32 v0, 4, v149
	s_add_u32 s5, s38, s66
	v_or_b32_e32 v98, s5, v0
	v_mov_b64_e32 v[66:67], s[12:13]
	s_addc_u32 s6, s39, s4
	v_mad_u64_u32 v[66:67], s[4:5], v98, s44, v[66:67]
	v_mad_i32_i24 v67, s6, v196, v67
	s_lshl_b32 s8, s67, 1
	v_lshl_add_u64 v[66:67], v[66:67], 0, s[8:9]
	v_mov_b32_e32 v149, v1
	v_lshl_add_u64 v[66:67], v[66:67], 0, v[148:149]
	v_add_co_u32_e32 v68, vcc, s50, v66
	s_mulk_i32 s64, 0x2200
	s_nop 0
	v_addc_co_u32_e32 v69, vcc, 0, v67, vcc
	v_add_co_u32_e32 v70, vcc, s51, v66
	s_add_i32 s4, s64, 0
	s_nop 0
	v_addc_co_u32_e32 v71, vcc, 0, v67, vcc
	global_load_dwordx4 v[90:93], v[68:69], off
	global_load_dwordx4 v[94:97], v[70:71], off
	v_add_co_u32_e32 v68, vcc, s52, v66
	v_add3_u32 v100, s4, v197, v151
	s_nop 0
	v_addc_co_u32_e32 v69, vcc, 0, v67, vcc
	v_add_co_u32_e32 v70, vcc, s53, v66
	v_cvt_pk_bf16_f32 v50, v50, v51
	s_nop 0
	v_addc_co_u32_e32 v71, vcc, 0, v67, vcc
	global_load_dwordx4 v[86:89], v[68:69], off
	global_load_dwordx4 v[82:85], v[70:71], off
	v_add_co_u32_e32 v68, vcc, s54, v66
	v_cvt_pk_bf16_f32 v51, v52, v53
	s_nop 0
	v_addc_co_u32_e32 v69, vcc, 0, v67, vcc
	v_add_co_u32_e32 v70, vcc, s55, v66
	v_cvt_pk_bf16_f32 v52, v54, v55
	s_nop 0
	v_addc_co_u32_e32 v71, vcc, 0, v67, vcc
	global_load_dwordx4 v[78:81], v[68:69], off
	global_load_dwordx4 v[74:77], v[70:71], off
	v_add_co_u32_e32 v68, vcc, s56, v66
	v_cvt_pk_bf16_f32 v53, v56, v57
	s_nop 0
	v_addc_co_u32_e32 v69, vcc, 0, v67, vcc
	v_add_co_u32_e32 v66, vcc, s57, v66
	v_cvt_pk_bf16_f32 v34, v34, v35
	s_nop 0
	v_addc_co_u32_e32 v67, vcc, 0, v67, vcc
	global_load_dwordx4 v[70:73], v[68:69], off
	s_nop 0
	global_load_dwordx4 v[66:69], v[66:67], off
	v_cvt_pk_bf16_f32 v35, v36, v37
	v_cvt_pk_bf16_f32 v36, v38, v39
	v_cvt_pk_bf16_f32 v37, v40, v41
	v_cvt_pk_bf16_f32 v18, v18, v19
	v_cvt_pk_bf16_f32 v19, v20, v21
	v_cvt_pk_bf16_f32 v20, v22, v23
	v_cvt_pk_bf16_f32 v21, v24, v25
	v_cvt_pk_bf16_f32 v2, v2, v3
	v_cvt_pk_bf16_f32 v3, v4, v5
	v_cvt_pk_bf16_f32 v4, v6, v7
	v_cvt_pk_bf16_f32 v5, v8, v9
	ds_write2_b64 v100, v[50:51], v[52:53] offset1:2
	v_cvt_pk_bf16_f32 v50, v58, v59
	v_cvt_pk_bf16_f32 v51, v60, v61
	v_cvt_pk_bf16_f32 v52, v62, v63
	v_cvt_pk_bf16_f32 v53, v64, v65
	ds_write2_b64 v100, v[34:35], v[36:37] offset0:8 offset1:10
	v_cvt_pk_bf16_f32 v34, v42, v43
	v_cvt_pk_bf16_f32 v35, v44, v45
	v_cvt_pk_bf16_f32 v36, v46, v47
	v_cvt_pk_bf16_f32 v37, v48, v49
	ds_write2_b64 v100, v[18:19], v[20:21] offset0:16 offset1:18
	v_cvt_pk_bf16_f32 v18, v26, v27
	v_cvt_pk_bf16_f32 v19, v28, v29
	v_cvt_pk_bf16_f32 v20, v30, v31
	v_cvt_pk_bf16_f32 v21, v32, v33
	ds_write2_b64 v100, v[2:3], v[4:5] offset0:24 offset1:26
	v_cvt_pk_bf16_f32 v2, v10, v11
	v_cvt_pk_bf16_f32 v3, v12, v13
	v_cvt_pk_bf16_f32 v4, v14, v15
	v_cvt_pk_bf16_f32 v5, v16, v17
	ds_write2_b64 v100, v[50:51], v[52:53] offset0:4 offset1:6
	ds_write2_b64 v100, v[34:35], v[36:37] offset0:12 offset1:14
	ds_write2_b64 v100, v[18:19], v[20:21] offset0:20 offset1:22
	ds_write2_b64 v100, v[2:3], v[4:5] offset0:28 offset1:30
	v_mul_u32_u24_e32 v0, 0x110, v0
	s_waitcnt lgkmcnt(0)
	v_add3_u32 v0, s4, v148, v0
	ds_read_b128 v[4:7], v0
	ds_read_b128 v[8:11], v0 offset:1088
	v_mov_b32_e32 v99, s6
	v_lshlrev_b64 v[2:3], 12, v[98:99]
	v_lshl_add_u64 v[2:3], s[10:11], 0, v[2:3]
	s_waitcnt lgkmcnt(1)
	v_lshlrev_b32_e32 v12, 16, v4
	v_and_b32_e32 v13, 0xffff0000, v4
	s_waitcnt vmcnt(7)
	v_lshlrev_b32_e32 v14, 16, v90
	v_and_b32_e32 v15, 0xffff0000, v90
	v_pk_mul_f32 v[12:13], v[14:15], v[12:13]
	v_lshlrev_b32_e32 v14, 16, v91
	v_cvt_pk_bf16_f32 v4, v12, v13
	v_lshlrev_b32_e32 v12, 16, v5
	v_and_b32_e32 v13, 0xffff0000, v5
	v_and_b32_e32 v15, 0xffff0000, v91
	v_pk_mul_f32 v[12:13], v[14:15], v[12:13]
	v_lshlrev_b32_e32 v14, 16, v92
	v_cvt_pk_bf16_f32 v5, v12, v13
	v_lshlrev_b32_e32 v12, 16, v6
	v_and_b32_e32 v13, 0xffff0000, v6
	v_and_b32_e32 v15, 0xffff0000, v92
	v_pk_mul_f32 v[12:13], v[14:15], v[12:13]
	v_lshlrev_b32_e32 v14, 16, v93
	v_cvt_pk_bf16_f32 v6, v12, v13
	v_lshlrev_b32_e32 v12, 16, v7
	v_and_b32_e32 v13, 0xffff0000, v7
	v_and_b32_e32 v15, 0xffff0000, v93
	v_lshl_add_u64 v[2:3], v[2:3], 0, s[8:9]
	v_pk_mul_f32 v[12:13], v[14:15], v[12:13]
	v_lshl_add_u64 v[2:3], v[2:3], 0, v[148:149]
	v_cvt_pk_bf16_f32 v7, v12, v13
	global_store_dwordx4 v[2:3], v[4:7], off
	v_add_co_u32_e32 v12, vcc, s58, v2
	s_waitcnt lgkmcnt(0)
	v_lshlrev_b32_e32 v4, 16, v8
	v_and_b32_e32 v5, 0xffff0000, v8
	s_waitcnt vmcnt(7)
	v_lshlrev_b32_e32 v6, 16, v94
	v_and_b32_e32 v7, 0xffff0000, v94
	v_pk_mul_f32 v[4:5], v[6:7], v[4:5]
	v_lshlrev_b32_e32 v6, 16, v9
	v_and_b32_e32 v7, 0xffff0000, v9
	v_lshlrev_b32_e32 v8, 16, v95
	v_and_b32_e32 v9, 0xffff0000, v95
	v_pk_mul_f32 v[6:7], v[8:9], v[6:7]
	v_cvt_pk_bf16_f32 v4, v4, v5
	v_cvt_pk_bf16_f32 v5, v6, v7
	v_lshlrev_b32_e32 v6, 16, v10
	v_and_b32_e32 v7, 0xffff0000, v10
	v_lshlrev_b32_e32 v8, 16, v96
	v_and_b32_e32 v9, 0xffff0000, v96
	v_pk_mul_f32 v[6:7], v[8:9], v[6:7]
	v_lshlrev_b32_e32 v8, 16, v11
	v_and_b32_e32 v9, 0xffff0000, v11
	v_lshlrev_b32_e32 v10, 16, v97
	v_and_b32_e32 v11, 0xffff0000, v97
	v_pk_mul_f32 v[8:9], v[10:11], v[8:9]
	v_cvt_pk_bf16_f32 v6, v6, v7
	v_cvt_pk_bf16_f32 v7, v8, v9
	ds_read_b128 v[8:11], v0 offset:2176
	v_addc_co_u32_e32 v13, vcc, 0, v3, vcc
	global_store_dwordx4 v[12:13], v[4:7], off
	ds_read_b128 v[4:7], v0 offset:3264
	s_waitcnt lgkmcnt(1)
	v_lshlrev_b32_e32 v12, 16, v8
	v_and_b32_e32 v13, 0xffff0000, v8
	s_waitcnt vmcnt(7)
	v_lshlrev_b32_e32 v14, 16, v86
	v_and_b32_e32 v15, 0xffff0000, v86
	v_pk_mul_f32 v[12:13], v[14:15], v[12:13]
	v_lshlrev_b32_e32 v14, 16, v87
	v_cvt_pk_bf16_f32 v8, v12, v13
	v_lshlrev_b32_e32 v12, 16, v9
	v_and_b32_e32 v13, 0xffff0000, v9
	v_and_b32_e32 v15, 0xffff0000, v87
	v_pk_mul_f32 v[12:13], v[14:15], v[12:13]
	v_lshlrev_b32_e32 v14, 16, v88
	v_cvt_pk_bf16_f32 v9, v12, v13
	v_lshlrev_b32_e32 v12, 16, v10
	v_and_b32_e32 v13, 0xffff0000, v10
	v_and_b32_e32 v15, 0xffff0000, v88
	v_pk_mul_f32 v[12:13], v[14:15], v[12:13]
	v_lshlrev_b32_e32 v14, 16, v89
	v_cvt_pk_bf16_f32 v10, v12, v13
	v_lshlrev_b32_e32 v12, 16, v11
	v_and_b32_e32 v13, 0xffff0000, v11
	v_and_b32_e32 v15, 0xffff0000, v89
	v_pk_mul_f32 v[12:13], v[14:15], v[12:13]
	s_waitcnt vmcnt(5)
	v_lshlrev_b32_e32 v14, 16, v78
	v_cvt_pk_bf16_f32 v11, v12, v13
	v_add_co_u32_e32 v12, vcc, s59, v2
	v_and_b32_e32 v15, 0xffff0000, v78
	s_nop 0
	v_addc_co_u32_e32 v13, vcc, 0, v3, vcc
	global_store_dwordx4 v[12:13], v[8:11], off
	v_add_co_u32_e32 v12, vcc, s45, v2
	s_waitcnt lgkmcnt(0)
	v_lshlrev_b32_e32 v8, 16, v4
	v_and_b32_e32 v9, 0xffff0000, v4
	v_lshlrev_b32_e32 v10, 16, v82
	v_and_b32_e32 v11, 0xffff0000, v82
	v_pk_mul_f32 v[8:9], v[10:11], v[8:9]
	v_lshlrev_b32_e32 v10, 16, v83
	v_cvt_pk_bf16_f32 v4, v8, v9
	v_lshlrev_b32_e32 v8, 16, v5
	v_and_b32_e32 v9, 0xffff0000, v5
	v_and_b32_e32 v11, 0xffff0000, v83
	v_pk_mul_f32 v[8:9], v[10:11], v[8:9]
	v_lshlrev_b32_e32 v10, 16, v84
	v_cvt_pk_bf16_f32 v5, v8, v9
	v_lshlrev_b32_e32 v8, 16, v6
	v_and_b32_e32 v9, 0xffff0000, v6
	v_and_b32_e32 v11, 0xffff0000, v84
	v_pk_mul_f32 v[8:9], v[10:11], v[8:9]
	v_lshlrev_b32_e32 v10, 16, v85
	v_cvt_pk_bf16_f32 v6, v8, v9
	v_lshlrev_b32_e32 v8, 16, v7
	v_and_b32_e32 v9, 0xffff0000, v7
	v_and_b32_e32 v11, 0xffff0000, v85
	v_pk_mul_f32 v[8:9], v[10:11], v[8:9]
	v_addc_co_u32_e32 v13, vcc, 0, v3, vcc
	v_cvt_pk_bf16_f32 v7, v8, v9
	ds_read_b128 v[8:11], v0 offset:4352
	global_store_dwordx4 v[12:13], v[4:7], off
	ds_read_b128 v[4:7], v0 offset:5440
	s_add_i32 s3, s3, s24
	s_xor_b32 s3, s3, 7
	s_add_i32 s63, s63, s24
	s_xor_b32 s63, s63, 7
	s_waitcnt lgkmcnt(1)
	v_lshlrev_b32_e32 v12, 16, v8
	v_and_b32_e32 v13, 0xffff0000, v8
	v_pk_mul_f32 v[12:13], v[14:15], v[12:13]
	v_lshlrev_b32_e32 v14, 16, v79
	v_cvt_pk_bf16_f32 v8, v12, v13
	v_lshlrev_b32_e32 v12, 16, v9
	v_and_b32_e32 v13, 0xffff0000, v9
	v_and_b32_e32 v15, 0xffff0000, v79
	v_pk_mul_f32 v[12:13], v[14:15], v[12:13]
	v_lshlrev_b32_e32 v14, 16, v80
	v_cvt_pk_bf16_f32 v9, v12, v13
	v_lshlrev_b32_e32 v12, 16, v10
	v_and_b32_e32 v13, 0xffff0000, v10
	v_and_b32_e32 v15, 0xffff0000, v80
	v_pk_mul_f32 v[12:13], v[14:15], v[12:13]
	v_lshlrev_b32_e32 v14, 16, v81
	v_cvt_pk_bf16_f32 v10, v12, v13
	v_lshlrev_b32_e32 v12, 16, v11
	v_and_b32_e32 v13, 0xffff0000, v11
	v_and_b32_e32 v15, 0xffff0000, v81
	v_pk_mul_f32 v[12:13], v[14:15], v[12:13]
	s_waitcnt vmcnt(5)
	v_lshlrev_b32_e32 v14, 16, v70
	v_cvt_pk_bf16_f32 v11, v12, v13
	v_add_co_u32_e32 v12, vcc, s60, v2
	v_and_b32_e32 v15, 0xffff0000, v70
	s_nop 0
	v_addc_co_u32_e32 v13, vcc, 0, v3, vcc
	global_store_dwordx4 v[12:13], v[8:11], off
	v_add_co_u32_e32 v12, vcc, s61, v2
	s_waitcnt lgkmcnt(0)
	v_lshlrev_b32_e32 v8, 16, v4
	v_and_b32_e32 v9, 0xffff0000, v4
	v_lshlrev_b32_e32 v10, 16, v74
	v_and_b32_e32 v11, 0xffff0000, v74
	v_pk_mul_f32 v[8:9], v[10:11], v[8:9]
	v_lshlrev_b32_e32 v10, 16, v75
	v_cvt_pk_bf16_f32 v4, v8, v9
	v_lshlrev_b32_e32 v8, 16, v5
	v_and_b32_e32 v9, 0xffff0000, v5
	v_and_b32_e32 v11, 0xffff0000, v75
	v_pk_mul_f32 v[8:9], v[10:11], v[8:9]
	v_lshlrev_b32_e32 v10, 16, v76
	v_cvt_pk_bf16_f32 v5, v8, v9
	v_lshlrev_b32_e32 v8, 16, v6
	v_and_b32_e32 v9, 0xffff0000, v6
	v_and_b32_e32 v11, 0xffff0000, v76
	v_pk_mul_f32 v[8:9], v[10:11], v[8:9]
	v_lshlrev_b32_e32 v10, 16, v77
	v_cvt_pk_bf16_f32 v6, v8, v9
	v_lshlrev_b32_e32 v8, 16, v7
	v_and_b32_e32 v9, 0xffff0000, v7
	v_and_b32_e32 v11, 0xffff0000, v77
	v_pk_mul_f32 v[8:9], v[10:11], v[8:9]
	v_addc_co_u32_e32 v13, vcc, 0, v3, vcc
	v_cvt_pk_bf16_f32 v7, v8, v9
	ds_read_b128 v[8:11], v0 offset:6528
	global_store_dwordx4 v[12:13], v[4:7], off
	ds_read_b128 v[4:7], v0 offset:7616
	s_cmpk_gt_i32 s3, 0x1ff
	s_waitcnt lgkmcnt(1)
	v_lshlrev_b32_e32 v12, 16, v8
	v_and_b32_e32 v13, 0xffff0000, v8
	v_pk_mul_f32 v[12:13], v[14:15], v[12:13]
	v_lshlrev_b32_e32 v14, 16, v71
	v_cvt_pk_bf16_f32 v8, v12, v13
	v_lshlrev_b32_e32 v12, 16, v9
	v_and_b32_e32 v13, 0xffff0000, v9
	v_and_b32_e32 v15, 0xffff0000, v71
	v_pk_mul_f32 v[12:13], v[14:15], v[12:13]
	v_lshlrev_b32_e32 v14, 16, v72
	v_cvt_pk_bf16_f32 v9, v12, v13
	v_lshlrev_b32_e32 v12, 16, v10
	v_and_b32_e32 v13, 0xffff0000, v10
	v_and_b32_e32 v15, 0xffff0000, v72
	v_pk_mul_f32 v[12:13], v[14:15], v[12:13]
	v_lshlrev_b32_e32 v14, 16, v73
	v_cvt_pk_bf16_f32 v10, v12, v13
	v_lshlrev_b32_e32 v12, 16, v11
	v_and_b32_e32 v13, 0xffff0000, v11
	v_and_b32_e32 v15, 0xffff0000, v73
	v_pk_mul_f32 v[12:13], v[14:15], v[12:13]
	s_nop 0
	v_cvt_pk_bf16_f32 v11, v12, v13
	v_add_co_u32_e32 v12, vcc, s62, v2
	s_nop 1
	v_addc_co_u32_e32 v13, vcc, 0, v3, vcc
	global_store_dwordx4 v[12:13], v[8:11], off
	v_add_co_u32_e32 v2, vcc, 0x1c000, v2
	s_waitcnt lgkmcnt(0)
	v_lshlrev_b32_e32 v8, 16, v4
	v_and_b32_e32 v9, 0xffff0000, v4
	s_waitcnt vmcnt(7)
	v_lshlrev_b32_e32 v10, 16, v66
	v_and_b32_e32 v11, 0xffff0000, v66
	v_pk_mul_f32 v[8:9], v[10:11], v[8:9]
	v_lshlrev_b32_e32 v10, 16, v67
	v_cvt_pk_bf16_f32 v4, v8, v9
	v_lshlrev_b32_e32 v8, 16, v5
	v_and_b32_e32 v9, 0xffff0000, v5
	v_and_b32_e32 v11, 0xffff0000, v67
	v_pk_mul_f32 v[8:9], v[10:11], v[8:9]
	v_lshlrev_b32_e32 v10, 16, v68
	v_cvt_pk_bf16_f32 v5, v8, v9
	v_lshlrev_b32_e32 v8, 16, v6
	v_and_b32_e32 v9, 0xffff0000, v6
	v_and_b32_e32 v11, 0xffff0000, v68
	v_pk_mul_f32 v[8:9], v[10:11], v[8:9]
	v_lshlrev_b32_e32 v10, 16, v69
	v_cvt_pk_bf16_f32 v6, v8, v9
	v_lshlrev_b32_e32 v8, 16, v7
	v_and_b32_e32 v9, 0xffff0000, v7
	v_and_b32_e32 v11, 0xffff0000, v69
	v_pk_mul_f32 v[8:9], v[10:11], v[8:9]
	v_addc_co_u32_e32 v3, vcc, 0, v3, vcc
	v_cvt_pk_bf16_f32 v7, v8, v9
	global_store_dwordx4 v[2:3], v[4:7], off
	s_cbranch_scc1 .LBB0_601
.LBB0_585:
	s_and_b32 s4, s63, 7
	s_lshl_b32 s5, s4, 2
	v_mov_b32_e32 v6, v225
	s_or_b32 s71, s5, 2
	s_and_b32 s42, s3, 7
	v_readfirstlane_b32 s5, v6
	s_ashr_i32 s64, s5, 6
	s_lshl_b32 s65, s4, 8
	s_ashr_i32 s4, s3, 6
	s_lshl_b32 s5, s42, 8
	s_lshl_b32 s66, s64, 5
	s_add_i32 s66, s66, s5
	s_ashr_i32 s5, s4, 31
	s_bfe_u32 s8, s3, 0x30003
	v_and_b32_e32 v7, 31, v6
	s_lshl_b64 s[38:39], s[4:5], 11
	s_lshl_b32 s4, s4, 3
	s_waitcnt vmcnt(2)
	v_or_b32_e32 v150, s66, v7
	s_or_b32 s4, s4, s8
	s_ashr_i32 s5, s4, 31
	v_ashrrev_i32_e32 v151, 31, v150
	s_lshl_b64 s[4:5], s[4:5], 19
	v_lshl_add_u64 v[2:3], s[38:39], 0, v[150:151]
	s_add_u32 s6, s14, s4
	v_mad_u64_u32 v[4:5], s[40:41], v2, s44, v[146:147]
	v_bfe_u32 v8, v6, 5, 1
	s_addc_u32 s7, s15, s5
	v_mad_i32_i24 v5, v3, s44, v5
	s_lshl_b32 s67, s8, 7
	s_lshl_b32 s8, s8, 8
	v_lshl_add_u64 v[2:3], v[4:5], 0, s[8:9]
	v_lshlrev_b32_e32 v0, 4, v8
	v_lshl_add_u64 v[2:3], v[2:3], 0, v[0:1]
	global_load_dwordx4 v[98:101], v[2:3], off
	global_load_dwordx4 v[102:105], v[2:3], off offset:32
	global_load_dwordx4 v[106:109], v[2:3], off offset:64
	global_load_dwordx4 v[110:113], v[2:3], off offset:96
	global_load_dwordx4 v[114:117], v[2:3], off offset:128
	global_load_dwordx4 v[118:121], v[2:3], off offset:160
	global_load_dwordx4 v[122:125], v[2:3], off offset:192
	global_load_dwordx4 v[126:129], v[2:3], off offset:224
	v_lshlrev_b32_e32 v2, 3, v6
	s_add_u32 s4, s81, s4
	v_ashrrev_i32_e32 v3, 31, v2
	s_addc_u32 s5, s82, s5
	v_lshlrev_b64 v[2:3], 1, v[2:3]
	v_mov_b32_e32 v228, v2
	v_add_u32_e32 v229, 0x2000, v2
	s_waitcnt vmcnt(9)
	s_mov_b64 s[90:91], s[4:5]
	v_lshl_add_u64 v[154:155], s[4:5], 0, v[2:3]
	s_lshl_b32 s4, s42, 16
	s_mov_b64 s[88:89], s[6:7]
	v_lshl_add_u64 v[152:153], s[6:7], 0, v[2:3]
	s_or_b32 s8, s4, 0xc000
	v_lshl_add_u64 v[2:3], v[152:153], 0, s[8:9]
	s_barrier
	v_lshl_add_u64 v[4:5], v[154:155], 0, s[8:9]
	global_load_dwordx4 v[130:133], v[2:3], off
	global_load_dwordx4 v[134:137], v[4:5], off
	v_add_co_u32_e32 v2, vcc, s46, v2
	v_and_b32_e32 v149, 63, v6
	s_nop 0
	v_addc_co_u32_e32 v3, vcc, 0, v3, vcc
	v_add_co_u32_e32 v4, vcc, s46, v4
	v_mul_u32_u24_e32 v197, 0x110, v7
	s_nop 0
	v_addc_co_u32_e32 v5, vcc, 0, v5, vcc
	global_load_dwordx4 v[138:141], v[2:3], off
	global_load_dwordx4 v[142:145], v[4:5], off
	v_lshlrev_b32_e32 v2, 4, v6
	v_lshrrev_b32_e32 v3, 3, v6
	v_lshrrev_b32_e32 v4, 4, v6
	v_and_b32_e32 v148, 0xf0, v2
	v_and_b32_e32 v2, 0x70, v2
	s_waitcnt vmcnt(12)
	v_mad_u64_u32 v[156:157], s[4:5], v4, s47, v[148:149]
	v_mad_u64_u32 v[158:159], s[4:5], v3, s48, v[2:3]
	v_lshlrev_b32_e32 v5, 7, v7
	v_add3_u32 v157, 0, v197, v0
	v_add_u32_e32 v0, 0, v156
	v_add_u32_e32 v2, 0, v158
	v_mov_b32_e32 v14, v1
	v_mov_b32_e32 v15, v1
	v_lshlrev_b32_e32 v151, 3, v8
	s_lshl_b32 s4, s64, 2
	v_lshlrev_b32_e32 v159, 2, v8
	v_sub_u32_e32 v198, v157, v5
	v_mov_b32_e32 v3, v1
	v_mov_b32_e32 v4, v1
	v_mov_b32_e32 v5, v1
	v_mov_b32_e32 v6, v1
	v_mov_b32_e32 v7, v1
	v_mov_b32_e32 v8, v1
	v_mov_b32_e32 v9, v1
	v_mov_b32_e32 v10, v1
	v_mov_b32_e32 v11, v1
	v_mov_b32_e32 v12, v1
	v_mov_b32_e32 v13, v1
	s_add_i32 s69, s4, 0
	v_cmp_eq_u32_e64 s[6:7], 0, v149
	s_or_b32 s68, s66, 30
	s_add_i32 s69, s69, 0x11800
	v_cmp_gt_u32_e64 s[4:5], 32, v149
	s_mov_b64 s[42:43], 0
	s_mov_b32 s70, s9
	s_mov_b32 s8, s71
	s_mov_b32 s71, s9
	s_waitcnt vmcnt(3)
	ds_write_b128 v0, v[130:133]
	s_waitcnt vmcnt(2)
	ds_write_b128 v2, v[134:137] offset:17408
	s_waitcnt vmcnt(1)
	ds_write_b128 v0, v[138:141] offset:8704
	s_waitcnt vmcnt(0)
	ds_write_b128 v2, v[142:145] offset:26624
	v_mov_b32_e32 v0, v1
	v_mov_b32_e32 v2, v1
	v_mov_b64_e32 v[64:65], v[14:15]
	v_mov_b64_e32 v[48:49], v[14:15]
	v_mov_b64_e32 v[32:33], v[14:15]
	v_mov_b64_e32 v[62:63], v[12:13]
	v_mov_b64_e32 v[60:61], v[10:11]
	v_mov_b64_e32 v[58:59], v[8:9]
	v_mov_b64_e32 v[56:57], v[6:7]
	v_mov_b64_e32 v[54:55], v[4:5]
	v_mov_b64_e32 v[52:53], v[2:3]
	v_mov_b64_e32 v[50:51], v[0:1]
	v_mov_b64_e32 v[46:47], v[12:13]
	v_mov_b64_e32 v[44:45], v[10:11]
	v_mov_b64_e32 v[42:43], v[8:9]
	v_mov_b64_e32 v[40:41], v[6:7]
	v_mov_b64_e32 v[38:39], v[4:5]
	v_mov_b64_e32 v[36:37], v[2:3]
	v_mov_b64_e32 v[34:35], v[0:1]
	v_mov_b64_e32 v[30:31], v[12:13]
	v_mov_b64_e32 v[28:29], v[10:11]
	v_mov_b64_e32 v[26:27], v[8:9]
	v_mov_b64_e32 v[24:25], v[6:7]
	v_mov_b64_e32 v[22:23], v[4:5]
	v_mov_b64_e32 v[20:21], v[2:3]
	v_mov_b64_e32 v[18:19], v[0:1]
	v_mov_b64_e32 v[16:17], v[14:15]
	v_mov_b64_e32 v[14:15], v[12:13]
	v_mov_b64_e32 v[12:13], v[10:11]
	v_mov_b64_e32 v[10:11], v[8:9]
	v_mov_b64_e32 v[8:9], v[6:7]
	v_mov_b64_e32 v[6:7], v[4:5]
	v_mov_b64_e32 v[4:5], v[2:3]
	v_mov_b64_e32 v[2:3], v[0:1]
	v_mov_b32_e32 v0, 0
	s_waitcnt lgkmcnt(0)
	s_barrier
	s_branch .LBB0_587
	s_nop 0
	s_nop 0
	s_nop 0
	s_nop 0
	s_nop 0
	s_nop 0
	s_nop 0
	s_nop 0
	s_nop 0
	s_nop 0
	s_nop 0
	s_nop 0
	s_nop 0
	s_nop 0
	s_nop 0
	s_nop 0
	s_nop 0
	s_nop 0
	s_nop 0
	s_nop 0
	s_nop 0
	s_nop 0
	s_nop 0
	s_nop 0
	s_nop 0
	s_nop 0
	s_nop 0
	s_nop 0
	s_nop 0
	s_nop 0
	s_nop 0
	s_nop 0
	s_nop 0
	s_nop 0
	s_nop 0
	s_nop 0
	s_nop 0
	s_nop 0
	s_nop 0
